# SEL loop: skip a 32-row half (QK, softmax, PV) when none of its rows selected the block
# speedup vs baseline: 1.0217x; 1.0017x over previous
.LBB0_630:
	s_lshl_b32 s74, s9, 7
	v_lshl_add_u64 v[66:67], v[182:183], 0, s[74:75]
	global_load_dwordx4 v[142:145], v[66:67], off
	global_load_dwordx4 v[138:141], v[66:67], off offset:2048
	global_load_dwordx4 v[134:137], v[66:67], off offset:1024
	global_load_dwordx4 v[130:133], v[66:67], off offset:3072
	s_cmp_eq_u64 s[6:7], 0
	s_cbranch_scc1 .Lsel_skip0
.Lsel_noskip0:
	s_waitcnt vmcnt(4)
	v_mfma_f32_32x32x16_bf16 v[66:81], v[118:121], v[82:85], 0
	v_mfma_f32_32x32x16_bf16 v[66:81], v[122:125], v[86:89], v[66:81]
	v_mfma_f32_32x32x16_bf16 v[66:81], v[126:129], v[90:93], v[66:81]
	v_mfma_f32_32x32x16_bf16 v[66:81], v[114:117], v[94:97], v[66:81]
	s_and_b64 vcc, exec, s[56:57]
	s_cbranch_vccnz .LBB0_632
	v_add_u32_e32 v186, s9, v173
	v_or_b32_e32 v202, 2, v186
	v_or_b32_e32 v200, 3, v186
	v_add_u32_e32 v192, 8, v186
	v_add_u32_e32 v201, 9, v186
	v_add_u32_e32 v193, 10, v186
	v_add_u32_e32 v191, 11, v186
	v_add_u32_e32 v190, 16, v186
	v_add_u32_e32 v189, 17, v186
	v_add_u32_e32 v188, 18, v186
	v_add_u32_e32 v187, 19, v186
	v_cmp_le_i32_e64 s[10:11], v186, v172
	v_cmp_lt_i32_e64 s[8:9], v186, v172
	v_cmp_le_i32_e64 s[30:31], v202, v172
	v_cmp_le_i32_e64 s[28:29], v200, v172
	v_cmp_le_i32_e64 s[26:27], v192, v172
	v_cmp_le_i32_e64 s[22:23], v201, v172
	v_cmp_le_i32_e64 s[18:19], v193, v172
	v_cmp_le_i32_e64 s[14:15], v191, v172
	v_cmp_le_i32_e64 s[12:13], v190, v172
	v_cmp_le_i32_e64 s[24:25], v189, v172
	v_cmp_le_i32_e64 s[20:21], v188, v172
	v_cmp_le_i32_e64 s[16:17], v187, v172
	s_and_b64 vcc, s[6:7], s[10:11]
	s_nop 6
	v_cndmask_b32_e32 v66, v248, v66, vcc
	s_and_b64 vcc, s[6:7], s[8:9]
	v_cndmask_b32_e32 v67, v248, v67, vcc
	s_and_b64 vcc, s[6:7], s[30:31]
	v_cndmask_b32_e32 v68, v248, v68, vcc
	s_and_b64 vcc, s[6:7], s[28:29]
	v_cndmask_b32_e32 v69, v248, v69, vcc
	s_and_b64 vcc, s[6:7], s[26:27]
	v_cndmask_b32_e32 v70, v248, v70, vcc
	s_and_b64 vcc, s[6:7], s[22:23]
	v_cndmask_b32_e32 v71, v248, v71, vcc
	s_and_b64 vcc, s[6:7], s[18:19]
	v_cndmask_b32_e32 v72, v248, v72, vcc
	s_and_b64 vcc, s[6:7], s[14:15]
	v_cndmask_b32_e32 v73, v248, v73, vcc
	s_and_b64 vcc, s[6:7], s[12:13]
	v_cndmask_b32_e32 v74, v248, v74, vcc
	s_and_b64 vcc, s[6:7], s[24:25]
	v_cndmask_b32_e32 v75, v248, v75, vcc
	s_and_b64 vcc, s[6:7], s[20:21]
	v_cndmask_b32_e32 v76, v248, v76, vcc
	s_and_b64 vcc, s[6:7], s[16:17]
	v_add_u32_e32 v0, 24, v186
	v_cndmask_b32_e32 v77, v248, v77, vcc
	v_cmp_le_i32_e32 vcc, v0, v172
	s_and_b64 vcc, s[6:7], vcc
	v_add_u32_e32 v0, 25, v186
	v_cndmask_b32_e32 v78, v248, v78, vcc
	v_cmp_le_i32_e32 vcc, v0, v172
	s_and_b64 vcc, s[6:7], vcc
	v_add_u32_e32 v0, 26, v186
	v_cndmask_b32_e32 v79, v248, v79, vcc
	v_cmp_le_i32_e32 vcc, v0, v172
	s_and_b64 vcc, s[6:7], vcc
	v_add_u32_e32 v0, 27, v186
	v_cndmask_b32_e32 v80, v248, v80, vcc
	v_cmp_le_i32_e32 vcc, v0, v172
	s_and_b64 vcc, s[6:7], vcc
	s_nop 0
	v_cndmask_b32_e32 v81, v248, v81, vcc

.Lsel_join0:
	v_add_f32_e32 v151, v151, v196
	v_cvt_pk_bf16_f32 v66, v204, v205
	v_cvt_pk_bf16_f32 v67, v206, v207
	v_cvt_pk_bf16_f32 v68, v208, v209
	v_cvt_pk_bf16_f32 v69, v210, v211
	v_cvt_pk_bf16_f32 v70, v212, v213
	v_cvt_pk_bf16_f32 v71, v214, v215
	v_cvt_pk_bf16_f32 v72, v216, v217
	v_cvt_pk_bf16_f32 v73, v218, v219
	s_waitcnt vmcnt(0) lgkmcnt(0)
	v_mfma_f32_32x32x16_bf16 v[50:65], v[142:145], v[66:69], v[50:65]
	s_lshl_b32 s8, s90, 5
	s_add_i32 s8, s8, s91
	s_lshl_b32 s98, s8, 7
	v_lshl_add_u64 v[220:221], v[240:241], 0, s[98:99]
	s_xor_b64 s[6:7], s[56:57], -1
	v_mfma_f32_32x32x16_bf16 v[34:49], v[134:137], v[66:69], v[34:49]
	s_andn2_b64 vcc, exec, s[6:7]
	v_mfma_f32_32x32x16_bf16 v[50:65], v[138:141], v[70:73], v[50:65]
	v_mfma_f32_32x32x16_bf16 v[34:49], v[130:133], v[70:73], v[34:49]
	s_cmp_eq_u64 s[4:5], 0
	s_cbranch_scc1 .Lsel_skip1
	v_mfma_f32_32x32x16_bf16 v[66:81], v[118:121], v[98:101], 0
	v_mfma_f32_32x32x16_bf16 v[66:81], v[122:125], v[102:105], v[66:81]
	v_mfma_f32_32x32x16_bf16 v[66:81], v[126:129], v[106:109], v[66:81]
	v_mfma_f32_32x32x16_bf16 v[66:81], v[114:117], v[110:113], v[66:81]
	global_load_dwordx4 v[118:121], v[220:221], off
	global_load_dwordx4 v[122:125], v[220:221], off offset:1024
	global_load_dwordx4 v[126:129], v[220:221], off offset:2048
	global_load_dwordx4 v[114:117], v[220:221], off offset:3072
	s_cbranch_vccnz .LBB0_637
	v_cmp_le_i32_e32 vcc, v186, v174
	s_and_b64 vcc, s[4:5], vcc
	s_nop 4
	v_cndmask_b32_e32 v66, v248, v66, vcc
	v_cmp_lt_i32_e32 vcc, v186, v174
	s_and_b64 vcc, s[4:5], vcc
	s_nop 0
	v_cndmask_b32_e32 v67, v248, v67, vcc
	v_cmp_le_i32_e32 vcc, v186, v175
	s_and_b64 vcc, s[4:5], vcc
	s_nop 0
	v_cndmask_b32_e32 v68, v248, v68, vcc
	v_cmp_le_i32_e32 vcc, v186, v184
	s_and_b64 vcc, s[4:5], vcc
	s_nop 0
	v_cndmask_b32_e32 v69, v248, v69, vcc
	v_cmp_le_i32_e32 vcc, v186, v172
	s_and_b64 vcc, s[4:5], vcc
	s_nop 0
	v_cndmask_b32_e32 v70, v248, v70, vcc
	v_cmp_lt_i32_e32 vcc, v186, v172
	s_and_b64 vcc, s[4:5], vcc
	s_nop 0
	v_cndmask_b32_e32 v71, v248, v71, vcc
	v_cmp_le_i32_e32 vcc, v202, v172
	s_and_b64 vcc, s[4:5], vcc
	s_nop 0
	v_cndmask_b32_e32 v72, v248, v72, vcc
	v_cmp_le_i32_e32 vcc, v200, v172
	s_and_b64 vcc, s[4:5], vcc
	s_nop 0
	v_cndmask_b32_e32 v73, v248, v73, vcc
	v_cmp_le_i32_e32 vcc, v192, v172
	s_and_b64 vcc, s[4:5], vcc
	s_nop 0
	v_cndmask_b32_e32 v74, v248, v74, vcc
	v_cmp_le_i32_e32 vcc, v201, v172
	s_and_b64 vcc, s[4:5], vcc
	s_nop 0
	v_cndmask_b32_e32 v75, v248, v75, vcc
	v_cmp_le_i32_e32 vcc, v193, v172
	s_and_b64 vcc, s[4:5], vcc
	s_nop 0
	v_cndmask_b32_e32 v76, v248, v76, vcc
	v_cmp_le_i32_e32 vcc, v191, v172
	s_and_b64 vcc, s[4:5], vcc
	s_nop 0
	v_cndmask_b32_e32 v77, v248, v77, vcc
	v_cmp_le_i32_e32 vcc, v190, v172
	s_and_b64 vcc, s[4:5], vcc
	s_nop 0
	v_cndmask_b32_e32 v78, v248, v78, vcc
	v_cmp_le_i32_e32 vcc, v189, v172
	s_and_b64 vcc, s[4:5], vcc
	s_nop 0
	v_cndmask_b32_e32 v79, v248, v79, vcc
	v_cmp_le_i32_e32 vcc, v188, v172
	s_and_b64 vcc, s[4:5], vcc
	s_nop 0
	v_cndmask_b32_e32 v80, v248, v80, vcc
	v_cmp_le_i32_e32 vcc, v187, v172
	s_and_b64 vcc, s[4:5], vcc
	s_nop 0
	v_cndmask_b32_e32 v81, v248, v81, vcc

.Lsel_join1:
	v_add_f32_e32 v150, v150, v186
	v_cvt_pk_bf16_f32 v66, v204, v205
	v_cvt_pk_bf16_f32 v67, v206, v207
	v_cvt_pk_bf16_f32 v68, v208, v209
	v_cvt_pk_bf16_f32 v69, v210, v211
	v_cvt_pk_bf16_f32 v70, v212, v213
	v_cvt_pk_bf16_f32 v71, v214, v215
	v_cvt_pk_bf16_f32 v72, v216, v217
	v_cvt_pk_bf16_f32 v73, v218, v219
	s_waitcnt vmcnt(4)
	v_mfma_f32_32x32x16_bf16 v[18:33], v[142:145], v[66:69], v[18:33]
	v_mfma_f32_32x32x16_bf16 v[2:17], v[134:137], v[66:69], v[2:17]
	v_mfma_f32_32x32x16_bf16 v[18:33], v[138:141], v[70:73], v[18:33]
	v_mfma_f32_32x32x16_bf16 v[2:17], v[130:133], v[70:73], v[2:17]
.Lsel_tail:
	s_xor_b64 s[4:5], s[96:97], -1
	s_and_b64 vcc, exec, s[4:5]
	s_cbranch_vccnz .LBB0_642
	s_mov_b32 s8, s90
	s_mov_b32 s4, s83
	s_branch .LBB0_626
.Lsel_skip0:
	s_and_b64 vcc, exec, s[56:57]
	s_cbranch_vccz .Lsel_noskip0
	s_lshl_b32 s8, s90, 5
	s_add_i32 s8, s8, s91
	s_lshl_b32 s98, s8, 7
	v_lshl_add_u64 v[220:221], v[240:241], 0, s[98:99]
	s_mov_b64 s[6:7], 0
	s_waitcnt vmcnt(4)
	v_mfma_f32_32x32x16_bf16 v[66:81], v[118:121], v[98:101], 0
	v_mfma_f32_32x32x16_bf16 v[66:81], v[122:125], v[102:105], v[66:81]
	v_mfma_f32_32x32x16_bf16 v[66:81], v[126:129], v[106:109], v[66:81]
	v_mfma_f32_32x32x16_bf16 v[66:81], v[114:117], v[110:113], v[66:81]
	global_load_dwordx4 v[118:121], v[220:221], off
	global_load_dwordx4 v[122:125], v[220:221], off offset:1024
	global_load_dwordx4 v[126:129], v[220:221], off offset:2048
	global_load_dwordx4 v[114:117], v[220:221], off offset:3072
	s_branch .LBB0_637
.Lsel_skip1:
	global_load_dwordx4 v[118:121], v[220:221], off
	global_load_dwordx4 v[122:125], v[220:221], off offset:1024
	global_load_dwordx4 v[126:129], v[220:221], off offset:2048
	global_load_dwordx4 v[114:117], v[220:221], off offset:3072
	s_branch .Lsel_tail
